# fast path v5: packed P kept out of place (tile-B K-fragment regs) so both row-sum chains ride in tile-B PV gaps and tile-B packing in tile-A PV gaps
# speedup vs baseline: 1.0137x; 1.0011x over previous
; #define MFMA32(a, b, c) __builtin_amdgcn_mfma_f32_32x32x16_bf16((a), (b), (c), 0, 0, 0)
; DI int crow(int r, int h) { return (r & 3) + 8 * (r >> 2) + 4 * h; }
; DI void attn_item(const Params& p, int g, int seq, int hd, int qt, int m, char* smem, int split_j, int sub) {
;     ...
;   auto compute = [&](int st, int buf) __attribute__((always_inline)) {
;     const int k0 = (tbase + st) * 32, h = h_, l31 = l31_;
;     const bf16_t* Kb = Ks + buf * 32 * 72; const bf16_t* Vb = Vs + buf * 128 * 40;
;     const int rmin = k0 - (qw0 + 31), rmax = k0 + 31 - qw0;
;     const bool farL = rmax <= -128, farR = rmin >= 128;
;     if (!farL && region == 0) { rescale(__builtin_amdgcn_exp2f(cneg)); region = 1; }
;     if (farR && region == 1) { rescale(__builtin_amdgcn_exp2f(-cpos)); region = 2; }
;     bf16x8 kf[4], vf[2][4];
; #pragma unroll
;     for (int s = 0; s < 4; ++s) kf[s] = *(const bf16x8*)(Kb + l31 * 72 + s * 16 + h * 8);
; #pragma unroll
;     for (int s2 = 0; s2 < 2; ++s2)
; #pragma unroll
;       for (int dt = 0; dt < 4; ++dt) vf[s2][dt] = *(const bf16x8*)(Vb + (dt * 32 + l31) * 40 + s2 * 16 + h * 8);
;     __builtin_amdgcn_sched_barrier(0);
;     f32x16 X;
; #pragma unroll
;     for (int r = 0; r < 16; ++r) X[r] = 0.f;
; #pragma unroll
;     for (int s = 0; s < 4; ++s) X = MFMA32(kf[s], qf[s], X);
;     if (farL || farR) {
; #pragma unroll
;       for (int r = 0; r < 16; ++r) X[r] = __builtin_amdgcn_exp2f(X[r]);
;     } else {
;       const int rel0 = k0 - (qw0 + l31) + 128;
; #pragma unroll
;       for (int r = 0; r < 16; ++r) { int idx = rel0 + crow(r, h); idx = idx < 0 ? 0 : (idx > 256 ? 256 : idx); X[r] = __builtin_amdgcn_exp2f(X[r] + tab[idx]); }
;     }
;     bf16x8 pf[2];
; #pragma unroll
;     for (int s2 = 0; s2 < 2; ++s2) {
;       u32x4 w; w.x = pk_bf16(X[8 * s2], X[8 * s2 + 1]); w.y = pk_bf16(X[8 * s2 + 2], X[8 * s2 + 3]); w.z = pk_bf16(X[8 * s2 + 4], X[8 * s2 + 5]); w.w = pk_bf16(X[8 * s2 + 6], X[8 * s2 + 7]);
;       ls2 += (f32x2){X[8 * s2], X[8 * s2 + 1]}; ls2 += (f32x2){X[8 * s2 + 2], X[8 * s2 + 3]};
;       ls2 += (f32x2){X[8 * s2 + 4], X[8 * s2 + 5]}; ls2 += (f32x2){X[8 * s2 + 6], X[8 * s2 + 7]};
;       pf[s2] = __builtin_bit_cast(bf16x8, w);
;     }
; #pragma unroll
;     for (int s2 = 0; s2 < 2; ++s2)
; #pragma unroll
;       for (int dt = 0; dt < 4; ++dt) O[dt] = MFMA32(pf[s2], vf[s2][dt], O[dt]);
;   };
.Lat2_fast:
	s_add_i32 s10, s6, -3
	s_and_b32 s16, s10, 2
	s_mul_i32 s10, s16, 0x1200
	s_mul_i32 s18, s16, 0x2800
	v_add_u32_e32 v192, s10, v191
	v_add_u32_e32 v244, s18, v196
	ds_read_b128 v[64:67], v192
	ds_read_b128 v[80:83], v192 offset:32
	ds_read_b128 v[84:87], v192 offset:64
	ds_read_b128 v[88:91], v192 offset:96
	ds_read_b128 v[220:223], v192 offset:4608
	ds_read_b128 v[224:227], v192 offset:4640
	ds_read_b128 v[236:239], v192 offset:4672
	ds_read_b128 v[240:243], v192 offset:4704
	ds_read_b128 v[156:159], v244 offset:18432
	ds_read_b128 v[160:163], v244 offset:20992
	ds_read_b128 v[164:167], v244 offset:23552
	ds_read_b128 v[152:155], v244 offset:26112
	s_waitcnt lgkmcnt(11)
	v_mfma_f32_32x32x16_bf16 v[64:79], v[64:67], v[104:107], 0
	s_waitcnt lgkmcnt(10)
	v_mfma_f32_32x32x16_bf16 v[64:79], v[80:83], v[108:111], v[64:79]
	s_waitcnt lgkmcnt(9)
	v_mfma_f32_32x32x16_bf16 v[64:79], v[84:87], v[112:115], v[64:79]
	s_waitcnt lgkmcnt(8)
	v_mfma_f32_32x32x16_bf16 v[64:79], v[88:91], v[116:119], v[64:79]
	ds_read_b128 v[148:151], v244 offset:18464
	ds_read_b128 v[144:147], v244 offset:21024
	ds_read_b128 v[136:139], v244 offset:23584
	ds_read_b128 v[140:143], v244 offset:26144
	s_waitcnt lgkmcnt(11)
	v_mfma_f32_32x32x16_bf16 v[80:95], v[220:223], v[104:107], 0
	s_waitcnt lgkmcnt(10)
	v_mfma_f32_32x32x16_bf16 v[80:95], v[224:227], v[108:111], v[80:95]
	v_exp_f32_e32 v64, v64
	v_exp_f32_e32 v65, v65
	v_exp_f32_e32 v66, v66
	v_exp_f32_e32 v67, v67
	v_exp_f32_e32 v68, v68
	v_exp_f32_e32 v69, v69
	s_waitcnt lgkmcnt(9)
	v_mfma_f32_32x32x16_bf16 v[80:95], v[236:239], v[112:115], v[80:95]
	v_exp_f32_e32 v70, v70
	v_exp_f32_e32 v71, v71
	v_exp_f32_e32 v72, v72
	v_exp_f32_e32 v73, v73
	v_exp_f32_e32 v74, v74
	v_exp_f32_e32 v75, v75
	s_waitcnt lgkmcnt(8)
	v_mfma_f32_32x32x16_bf16 v[80:95], v[240:243], v[116:119], v[80:95]
	v_exp_f32_e32 v76, v76
	v_exp_f32_e32 v77, v77
	v_exp_f32_e32 v78, v78
	v_exp_f32_e32 v79, v79
	v_cvt_pk_bf16_f32 v220, v64, v65
	v_cvt_pk_bf16_f32 v221, v66, v67
	v_cvt_pk_bf16_f32 v222, v68, v69
	v_cvt_pk_bf16_f32 v223, v70, v71
	v_cvt_pk_bf16_f32 v224, v72, v73
	v_cvt_pk_bf16_f32 v225, v74, v75
	v_cvt_pk_bf16_f32 v226, v76, v77
	v_cvt_pk_bf16_f32 v227, v78, v79
	s_waitcnt lgkmcnt(7)
	v_mfma_f32_32x32x16_bf16 v[48:63], v[220:223], v[156:159], v[48:63]
	ds_read_b128 v[156:159], v244 offset:28672
	v_exp_f32_e32 v80, v80
	v_exp_f32_e32 v81, v81
	v_exp_f32_e32 v82, v82
	s_waitcnt lgkmcnt(7)
	v_mfma_f32_32x32x16_bf16 v[32:47], v[220:223], v[160:163], v[32:47]
	ds_read_b128 v[160:163], v244 offset:31232
	v_exp_f32_e32 v83, v83
	v_exp_f32_e32 v84, v84
	v_exp_f32_e32 v85, v85
	s_waitcnt lgkmcnt(7)
	v_mfma_f32_32x32x16_bf16 v[16:31], v[220:223], v[164:167], v[16:31]
	ds_read_b128 v[164:167], v244 offset:33792
	v_exp_f32_e32 v86, v86
	v_exp_f32_e32 v87, v87
	v_exp_f32_e32 v88, v88
	s_waitcnt lgkmcnt(7)
	v_mfma_f32_32x32x16_bf16 v[0:15], v[220:223], v[152:155], v[0:15]
	ds_read_b128 v[152:155], v244 offset:36352
	v_exp_f32_e32 v89, v89
	v_exp_f32_e32 v90, v90
	v_exp_f32_e32 v91, v91
	s_waitcnt lgkmcnt(7)
	v_mfma_f32_32x32x16_bf16 v[48:63], v[224:227], v[148:151], v[48:63]
	ds_read_b128 v[148:151], v244 offset:28704
	v_exp_f32_e32 v92, v92
	v_exp_f32_e32 v93, v93
	v_exp_f32_e32 v94, v94
	v_exp_f32_e32 v95, v95
	s_waitcnt lgkmcnt(7)
	v_mfma_f32_32x32x16_bf16 v[32:47], v[224:227], v[144:147], v[32:47]
	ds_read_b128 v[144:147], v244 offset:31264
	v_cvt_pk_bf16_f32 v236, v80, v81
	v_cvt_pk_bf16_f32 v237, v82, v83
	v_cvt_pk_bf16_f32 v238, v84, v85
	s_waitcnt lgkmcnt(7)
	v_mfma_f32_32x32x16_bf16 v[16:31], v[224:227], v[136:139], v[16:31]
	ds_read_b128 v[136:139], v244 offset:33824
	v_cvt_pk_bf16_f32 v239, v86, v87
	v_cvt_pk_bf16_f32 v240, v88, v89
	v_cvt_pk_bf16_f32 v241, v90, v91
	s_waitcnt lgkmcnt(7)
	v_mfma_f32_32x32x16_bf16 v[0:15], v[224:227], v[140:143], v[0:15]
	ds_read_b128 v[140:143], v244 offset:36384
	v_cvt_pk_bf16_f32 v242, v92, v93
	v_cvt_pk_bf16_f32 v243, v94, v95
	s_andn2_b64 vcc, exec, s[8:9]
	s_cbranch_vccnz .Lat2_pvplain
	s_xor_b32 s7, s16, 2
	s_mul_i32 s8, s7, 0x2800
	s_add_i32 s8, s8, 32
	s_mulk_i32 s7, 0x1200
	v_add_u32_e32 v192, s7, v169
	v_add3_u32 v244, s8, v189, v190
	s_addk_i32 s8, 0x2800
	s_waitcnt lgkmcnt(7)
	v_mfma_f32_32x32x16_bf16 v[48:63], v[236:239], v[156:159], v[48:63]
	s_waitcnt vmcnt(5)
	ds_write_b128 v192, v[96:99]
	v_pk_add_f32 v[246:247], v[66:67], v[70:71]
	v_pk_add_f32 v[186:187], v[186:187], v[64:65]
	s_waitcnt lgkmcnt(7)
	v_mfma_f32_32x32x16_bf16 v[32:47], v[236:239], v[160:163], v[32:47]
	s_waitcnt vmcnt(4)
	ds_write_b128 v244, v[100:103] offset:18432
	v_pk_add_f32 v[246:247], v[246:247], v[74:75]
	v_pk_add_f32 v[186:187], v[186:187], v[68:69]
	s_waitcnt lgkmcnt(7)
	v_mfma_f32_32x32x16_bf16 v[16:31], v[236:239], v[164:167], v[16:31]
	s_waitcnt vmcnt(3)
	ds_write_b128 v244, v[120:123] offset:23552
	v_pk_add_f32 v[246:247], v[246:247], v[78:79]
	v_pk_add_f32 v[186:187], v[186:187], v[72:73]
	s_waitcnt lgkmcnt(7)
	v_mfma_f32_32x32x16_bf16 v[0:15], v[236:239], v[152:155], v[0:15]
	s_waitcnt vmcnt(2)
	ds_write_b128 v192, v[124:127] offset:4608
	v_pk_add_f32 v[186:187], v[186:187], v[76:77]
	v_pk_add_f32 v[186:187], v[186:187], v[246:247]
	s_waitcnt lgkmcnt(7)
	v_mfma_f32_32x32x16_bf16 v[48:63], v[240:243], v[148:151], v[48:63]
	v_add3_u32 v192, s8, v189, v190
	s_waitcnt vmcnt(1)
	ds_write_b128 v192, v[128:131] offset:18432
	v_pk_add_f32 v[246:247], v[82:83], v[86:87]
	v_pk_add_f32 v[186:187], v[186:187], v[80:81]
	s_waitcnt lgkmcnt(7)
	v_mfma_f32_32x32x16_bf16 v[32:47], v[240:243], v[144:147], v[32:47]
	s_waitcnt vmcnt(0)
	ds_write_b128 v192, v[132:135] offset:23552
	v_pk_add_f32 v[246:247], v[246:247], v[90:91]
	v_pk_add_f32 v[186:187], v[186:187], v[84:85]
	s_waitcnt lgkmcnt(7)
	v_mfma_f32_32x32x16_bf16 v[16:31], v[240:243], v[136:139], v[16:31]
	v_pk_add_f32 v[246:247], v[246:247], v[94:95]
	v_pk_add_f32 v[186:187], v[186:187], v[88:89]
	s_waitcnt lgkmcnt(6)
	v_mfma_f32_32x32x16_bf16 v[0:15], v[240:243], v[140:143], v[0:15]
	v_pk_add_f32 v[186:187], v[186:187], v[92:93]
	v_pk_add_f32 v[186:187], v[186:187], v[246:247]
	s_branch .Lat2_bot
; DI void attn_item(const Params& p, int g, int seq, int hd, int qt, int m, char* smem, int split_j, int sub) {
;     ...
;   auto compute = [&](int st, int buf) __attribute__((always_inline)) {
;     const int k0 = (tbase + st) * 32, h = h_, l31 = l31_;
;     const bf16_t* Kb = Ks + buf * 32 * 72; const bf16_t* Vb = Vs + buf * 128 * 40;
;     const int rmin = k0 - (qw0 + 31), rmax = k0 + 31 - qw0;
;     const bool farL = rmax <= -128, farR = rmin >= 128;
;     if (!farL && region == 0) { rescale(__builtin_amdgcn_exp2f(cneg)); region = 1; }
;     if (farR && region == 1) { rescale(__builtin_amdgcn_exp2f(-cpos)); region = 2; }
;     bf16x8 kf[4], vf[2][4];
; #pragma unroll
;     for (int s = 0; s < 4; ++s) kf[s] = *(const bf16x8*)(Kb + l31 * 72 + s * 16 + h * 8);
; #pragma unroll
;     for (int s2 = 0; s2 < 2; ++s2)
; #pragma unroll
;       for (int dt = 0; dt < 4; ++dt) vf[s2][dt] = *(const bf16x8*)(Vb + (dt * 32 + l31) * 40 + s2 * 16 + h * 8);
;     __builtin_amdgcn_sched_barrier(0);
;     f32x16 X;
; #pragma unroll
;     for (int r = 0; r < 16; ++r) X[r] = 0.f;
; #pragma unroll
;     for (int s = 0; s < 4; ++s) X = MFMA32(kf[s], qf[s], X);
;     if (farL || farR) {
; #pragma unroll
;       for (int r = 0; r < 16; ++r) X[r] = __builtin_amdgcn_exp2f(X[r]);
;     } else {
;       const int rel0 = k0 - (qw0 + l31) + 128;
; #pragma unroll
;       for (int r = 0; r < 16; ++r) { int idx = rel0 + crow(r, h); idx = idx < 0 ? 0 : (idx > 256 ? 256 : idx); X[r] = __builtin_amdgcn_exp2f(X[r] + tab[idx]); }
;     }
;     bf16x8 pf[2];
; #pragma unroll
;     for (int s2 = 0; s2 < 2; ++s2) {
;       u32x4 w; w.x = pk_bf16(X[8 * s2], X[8 * s2 + 1]); w.y = pk_bf16(X[8 * s2 + 2], X[8 * s2 + 3]); w.z = pk_bf16(X[8 * s2 + 4], X[8 * s2 + 5]); w.w = pk_bf16(X[8 * s2 + 6], X[8 * s2 + 7]);
;       ls2 += (f32x2){X[8 * s2], X[8 * s2 + 1]}; ls2 += (f32x2){X[8 * s2 + 2], X[8 * s2 + 3]};
;       ls2 += (f32x2){X[8 * s2 + 4], X[8 * s2 + 5]}; ls2 += (f32x2){X[8 * s2 + 6], X[8 * s2 + 7]};
;       pf[s2] = __builtin_bit_cast(bf16x8, w);
;     }
; #pragma unroll
;     for (int s2 = 0; s2 < 2; ++s2)
; #pragma unroll
;       for (int dt = 0; dt < 4; ++dt) O[dt] = MFMA32(pf[s2], vf[s2][dt], O[dt]);
;   };
;   load_tile(0, rkA, rvA0, rvA1);
;   load_tile(1, rkB, rvB0, rvB1);
;   __syncthreads();
;   store_tile(0, rkA, rvA0, rvA1);
;   store_tile(1, rkB, rvB0, rvB1);
;   __syncthreads();
.Lat2_pvplain:
	s_waitcnt lgkmcnt(7)
	v_mfma_f32_32x32x16_bf16 v[48:63], v[236:239], v[156:159], v[48:63]
	v_pk_add_f32 v[246:247], v[66:67], v[70:71]
	v_pk_add_f32 v[186:187], v[186:187], v[64:65]
	s_waitcnt lgkmcnt(6)
	v_mfma_f32_32x32x16_bf16 v[32:47], v[236:239], v[160:163], v[32:47]
	v_pk_add_f32 v[246:247], v[246:247], v[74:75]
	v_pk_add_f32 v[186:187], v[186:187], v[68:69]
	s_waitcnt lgkmcnt(5)
	v_mfma_f32_32x32x16_bf16 v[16:31], v[236:239], v[164:167], v[16:31]
	v_pk_add_f32 v[246:247], v[246:247], v[78:79]
	v_pk_add_f32 v[186:187], v[186:187], v[72:73]
	s_waitcnt lgkmcnt(4)
	v_mfma_f32_32x32x16_bf16 v[0:15], v[236:239], v[152:155], v[0:15]
	v_pk_add_f32 v[186:187], v[186:187], v[76:77]
	v_pk_add_f32 v[186:187], v[186:187], v[246:247]
	s_waitcnt lgkmcnt(3)
	v_mfma_f32_32x32x16_bf16 v[48:63], v[240:243], v[148:151], v[48:63]
	v_pk_add_f32 v[246:247], v[82:83], v[86:87]
	v_pk_add_f32 v[186:187], v[186:187], v[80:81]
	s_waitcnt lgkmcnt(2)
	v_mfma_f32_32x32x16_bf16 v[32:47], v[240:243], v[144:147], v[32:47]
	v_pk_add_f32 v[246:247], v[246:247], v[90:91]
	v_pk_add_f32 v[186:187], v[186:187], v[84:85]
	s_waitcnt lgkmcnt(1)
	v_mfma_f32_32x32x16_bf16 v[16:31], v[240:243], v[136:139], v[16:31]
	v_pk_add_f32 v[246:247], v[246:247], v[94:95]
	v_pk_add_f32 v[186:187], v[186:187], v[88:89]
	s_waitcnt lgkmcnt(0)
	v_mfma_f32_32x32x16_bf16 v[0:15], v[240:243], v[140:143], v[0:15]
	v_pk_add_f32 v[186:187], v[186:187], v[92:93]
	v_pk_add_f32 v[186:187], v[186:187], v[246:247]
.Lat2_bot:
	s_add_i32 s13, s13, 64
	s_add_i32 s6, s6, 2
	s_cmp_lg_u32 s73, s15
	s_cbranch_scc0 .Lat2_exit
	s_add_i32 s15, s15, 1
	s_cmp_lt_u32 s15, s73
	s_cselect_b64 s[8:9], -1, 0
	s_cmp_ge_u32 s15, s73
	s_cbranch_scc1 .Lat2_nopf
	s_add_i32 s50, s6, -1
	s_lshl_b64 s[10:11], s[50:51], 12
	v_lshl_add_u64 v[220:221], v[172:173], 0, s[10:11]
	s_lshl_b64 s[10:11], s[50:51], 13
	v_lshl_add_u64 v[222:223], v[170:171], 0, s[10:11]
	s_mov_b32 s7, s51
	global_load_dwordx4 v[96:99], v[220:221], off
	global_load_dwordx4 v[100:103], v[222:223], off
	v_add_co_u32_e32 v220, vcc, 0x1000, v222
	s_lshl_b64 s[10:11], s[6:7], 12
	s_nop 0
	v_addc_co_u32_e32 v221, vcc, 0, v223, vcc
	v_lshl_add_u64 v[222:223], v[172:173], 0, s[10:11]
	s_lshl_b64 s[10:11], s[6:7], 13
	global_load_dwordx4 v[120:123], v[220:221], off
	global_load_dwordx4 v[124:127], v[222:223], off
	v_lshl_add_u64 v[220:221], v[170:171], 0, s[10:11]
	v_add_co_u32_e32 v222, vcc, 0x1000, v220
	s_nop 1
	v_addc_co_u32_e32 v223, vcc, 0, v221, vcc
	global_load_dwordx4 v[128:131], v[220:221], off
	global_load_dwordx4 v[132:135], v[222:223], off
